# l0_prep depthwise conv: per-thread weights kept in registers, the four tap loads of an item issued together (was one load-wait-fma ladder per tap)
# speedup vs baseline: 1.0079x; 1.0003x over previous
; DI unsigned pk2(float lo, float hi) { f32x2 v = {lo, hi}; bf16x2_t b = __builtin_convertvector(v, bf16x2_t); return __builtin_bit_cast(unsigned, b); }
; DI float bflo(unsigned u) { return __uint_as_float(u << 16); }
; DI float bfhi(unsigned u) { return __uint_as_float(u & 0xffff0000u); }
; DI void phase_l0_prep(int wv, const ArgP a) {
;     ...
; #pragma unroll 2
;     for (int e = blockIdx.x * 512 + tid; e < S * 64; e += gridDim.x * 512) { const int t = e >> 6, c0 = (e & 63) * 8;
;         float acc[8];
; #pragma unroll
;         for (int j = 0; j < 8; ++j) acc[j] = cb[c0 + j];
; #pragma unroll
;         for (int k = 0; k < 4; ++k) { const int tt = t - 3 + k; if (tt < 0) continue;
;             const u32x4 v = *(const u32x4*)(Z + (size_t)tt * 1536 + c0);
;             const f32x4 w0 = *(const f32x4*)(cw + k * 512 + c0), w1 = *(const f32x4*)(cw + k * 512 + c0 + 4);
;             acc[0] += w0[0] * bflo(v.x); acc[1] += w0[1] * bfhi(v.x); acc[2] += w0[2] * bflo(v.y); acc[3] += w0[3] * bfhi(v.y);
;             acc[4] += w1[0] * bflo(v.z); acc[5] += w1[1] * bfhi(v.z); acc[6] += w1[2] * bflo(v.w); acc[7] += w1[3] * bfhi(v.w); }
;         u32x4 o; o.x = pk2(acc[0], acc[1]); o.y = pk2(acc[2], acc[3]); o.z = pk2(acc[4], acc[5]); o.w = pk2(acc[6], acc[7]);
;         *(u32x4*)(XC + (size_t)t * 512 + c0) = o; }
.LBB0_441:
	s_or_b64 exec, exec, s[0:1]
	s_mov_b64 s[12:13], s[82:83]
	s_waitcnt lgkmcnt(0)
	s_barrier
	s_load_dwordx2 s[0:1], s[12:13], 0xe8
	s_mov_b32 s4, s50
	v_mov_b32_e32 v18, v192
	s_waitcnt lgkmcnt(0)
	s_add_u32 s2, s0, 0x556b000
	v_lshl_add_u32 v19, s4, 6, v18
	v_add_u32_e32 v21, s33, v19
	s_mov_b32 s22, 0x100000
	s_addc_u32 s3, s1, 0
	v_cmp_gt_i32_e32 vcc, s22, v21
	s_and_saveexec_b64 s[8:9], vcc
	s_cbranch_execz .LBB0_462
	s_load_dword s14, s[88:89], 0x0
	s_load_dwordx4 s[4:7], s[12:13], 0x20
	s_add_u32 s10, s0, 0x856b000
	s_addc_u32 s11, s1, 0
	v_lshlrev_b32_e32 v20, 3, v21
	v_and_b32_e32 v10, 0x1f8, v20
	v_lshlrev_b32_e32 v8, 2, v10
	v_lshlrev_b32_e32 v10, 1, v10
	s_movk_i32 s25, 0xc00
	s_waitcnt lgkmcnt(0)
	s_add_u32 s12, s4, 0x1000
	s_addc_u32 s13, s5, 0
	s_lshl_b32 s23, s14, 9
	global_load_dwordx4 v[40:43], v8, s[4:5]
	global_load_dwordx4 v[44:47], v8, s[4:5] offset:16
	global_load_dwordx4 v[48:51], v8, s[4:5] offset:2048
	global_load_dwordx4 v[52:55], v8, s[4:5] offset:2064
	global_load_dwordx4 v[56:59], v8, s[12:13]
	global_load_dwordx4 v[60:63], v8, s[12:13] offset:16
	global_load_dwordx4 v[64:67], v8, s[12:13] offset:2048
	global_load_dwordx4 v[68:71], v8, s[12:13] offset:2064
	global_load_dwordx4 v[72:75], v8, s[6:7]
	global_load_dwordx4 v[76:79], v8, s[6:7] offset:16
.Ll0c_loop:
	v_ashrrev_i32_e32 v16, 6, v21
	v_add_u32_e32 v11, -3, v16
	v_add_u32_e32 v13, -2, v16
	v_add_u32_e32 v14, -1, v16
	v_max_i32_e32 v12, 0, v11
	v_max_i32_e32 v13, 0, v13
	v_max_i32_e32 v14, 0, v14
	v_mad_u32_u24 v12, v12, s25, v10
	v_mad_u32_u24 v13, v13, s25, v10
	v_mad_u32_u24 v14, v14, s25, v10
	v_mad_u32_u24 v15, v16, s25, v10
	global_load_dwordx4 v[80:83], v12, s[2:3]
	global_load_dwordx4 v[84:87], v13, s[2:3]
	global_load_dwordx4 v[88:91], v14, s[2:3]
	global_load_dwordx4 v[92:95], v15, s[2:3]
	v_lshl_add_u32 v17, v16, 10, v10
	v_cmp_gt_i32_e32 vcc, 3, v16
	s_waitcnt vmcnt(0)
	v_mov_b32_e32 v24, v72
	v_mov_b32_e32 v25, v73
	v_mov_b32_e32 v26, v74
	v_mov_b32_e32 v27, v75
	v_mov_b32_e32 v28, v76
	v_mov_b32_e32 v29, v77
	v_mov_b32_e32 v30, v78
	v_mov_b32_e32 v31, v79
	s_cbranch_vccnz .Ll0c_edge
.Ll0c_taps:
	v_lshlrev_b32_e32 v100, 16, v80
	v_and_b32_e32 v101, 0xffff0000, v80
	v_lshlrev_b32_e32 v102, 16, v81
	v_and_b32_e32 v103, 0xffff0000, v81
	v_lshlrev_b32_e32 v104, 16, v82
	v_and_b32_e32 v105, 0xffff0000, v82
	v_lshlrev_b32_e32 v106, 16, v83
	v_and_b32_e32 v107, 0xffff0000, v83
	v_pk_fma_f32 v[24:25], v[40:41], v[100:101], v[24:25]
	v_pk_fma_f32 v[26:27], v[42:43], v[102:103], v[26:27]
	v_pk_fma_f32 v[28:29], v[44:45], v[104:105], v[28:29]
	v_pk_fma_f32 v[30:31], v[46:47], v[106:107], v[30:31]
	v_lshlrev_b32_e32 v100, 16, v84
	v_and_b32_e32 v101, 0xffff0000, v84
	v_lshlrev_b32_e32 v102, 16, v85
	v_and_b32_e32 v103, 0xffff0000, v85
	v_lshlrev_b32_e32 v104, 16, v86
	v_and_b32_e32 v105, 0xffff0000, v86
	v_lshlrev_b32_e32 v106, 16, v87
	v_and_b32_e32 v107, 0xffff0000, v87
	v_pk_fma_f32 v[24:25], v[48:49], v[100:101], v[24:25]
	v_pk_fma_f32 v[26:27], v[50:51], v[102:103], v[26:27]
	v_pk_fma_f32 v[28:29], v[52:53], v[104:105], v[28:29]
	v_pk_fma_f32 v[30:31], v[54:55], v[106:107], v[30:31]
	v_lshlrev_b32_e32 v100, 16, v88
	v_and_b32_e32 v101, 0xffff0000, v88
	v_lshlrev_b32_e32 v102, 16, v89
	v_and_b32_e32 v103, 0xffff0000, v89
	v_lshlrev_b32_e32 v104, 16, v90
	v_and_b32_e32 v105, 0xffff0000, v90
	v_lshlrev_b32_e32 v106, 16, v91
	v_and_b32_e32 v107, 0xffff0000, v91
	v_pk_fma_f32 v[24:25], v[56:57], v[100:101], v[24:25]
	v_pk_fma_f32 v[26:27], v[58:59], v[102:103], v[26:27]
	v_pk_fma_f32 v[28:29], v[60:61], v[104:105], v[28:29]
	v_pk_fma_f32 v[30:31], v[62:63], v[106:107], v[30:31]
	v_lshlrev_b32_e32 v100, 16, v92
	v_and_b32_e32 v101, 0xffff0000, v92
	v_lshlrev_b32_e32 v102, 16, v93
	v_and_b32_e32 v103, 0xffff0000, v93
	v_lshlrev_b32_e32 v104, 16, v94
	v_and_b32_e32 v105, 0xffff0000, v94
	v_lshlrev_b32_e32 v106, 16, v95
	v_and_b32_e32 v107, 0xffff0000, v95
	v_pk_fma_f32 v[24:25], v[64:65], v[100:101], v[24:25]
	v_pk_fma_f32 v[26:27], v[66:67], v[102:103], v[26:27]
	v_pk_fma_f32 v[28:29], v[68:69], v[104:105], v[28:29]
	v_pk_fma_f32 v[30:31], v[70:71], v[106:107], v[30:31]
	v_cvt_pk_bf16_f32 v108, v24, v25
	v_cvt_pk_bf16_f32 v109, v26, v27
	v_cvt_pk_bf16_f32 v110, v28, v29
	v_cvt_pk_bf16_f32 v111, v30, v31
	v_add_u32_e32 v21, s23, v21
	global_store_dwordx4 v17, v[108:111], s[10:11]
	v_cmp_gt_i32_e32 vcc, s22, v21
	s_nop 1
	s_and_b64 exec, exec, vcc
	s_cbranch_execnz .Ll0c_loop
	s_branch .LBB0_462
.Ll0c_edge:
	v_cmp_gt_i32_e64 s[18:19], 3, v16
	s_nop 1
	v_cndmask_b32_e64 v80, v80, 0, s[18:19]
	v_cndmask_b32_e64 v81, v81, 0, s[18:19]
	v_cndmask_b32_e64 v82, v82, 0, s[18:19]
	v_cndmask_b32_e64 v83, v83, 0, s[18:19]
	v_cmp_gt_i32_e64 s[18:19], 2, v16
	s_nop 1
	v_cndmask_b32_e64 v84, v84, 0, s[18:19]
	v_cndmask_b32_e64 v85, v85, 0, s[18:19]
	v_cndmask_b32_e64 v86, v86, 0, s[18:19]
	v_cndmask_b32_e64 v87, v87, 0, s[18:19]
	v_cmp_gt_i32_e64 s[18:19], 1, v16
	s_nop 1
	v_cndmask_b32_e64 v88, v88, 0, s[18:19]
	v_cndmask_b32_e64 v89, v89, 0, s[18:19]
	v_cndmask_b32_e64 v90, v90, 0, s[18:19]
	v_cndmask_b32_e64 v91, v91, 0, s[18:19]
	s_branch .Ll0c_taps
